# P4: logical wave ids 4-7 reversed so each SIMD pairs a light and a heavy causal row-block (9 key-blocks per SIMD)
# baseline (speedup 1.0000x reference)
.LBB0_717:
	v_bfe_u32 v247, v202, 8, 1
	v_mul_u32_u24_e32 v247, 0xc0, v247
	v_xor_b32_e32 v202, v202, v247
	v_readlane_b32 s4, v246, 4
	v_readlane_b32 s5, v246, 5
	s_cmp_lt_i32 s4, 5
	s_cselect_b64 s[4:5], -1, 0
	v_writelane_b32 v244, s4, 52
	s_and_b64 s[0:1], s[4:5], s[0:1]
	s_andn2_b64 vcc, exec, s[0:1]
	v_writelane_b32 v244, s5, 53
	s_cbranch_vccnz .LBB0_816
	s_cmpk_lt_i32 s30, 0xf8
	s_cselect_b64 s[4:5], -1, 0
	s_or_b64 s[4:5], s[4:5], s[2:3]
	s_mov_b64 s[0:1], -1
	s_and_b64 vcc, exec, s[4:5]
	v_writelane_b32 v244, s68, 54
	s_nop 1
	v_writelane_b32 v244, s69, 55
	s_cbranch_vccz .LBB0_770
	s_and_b64 vcc, exec, s[2:3]
	s_cbranch_vccz .LBB0_744
	s_cmpk_gt_i32 s30, 0x7ff
	s_cbranch_scc1 .LBB0_743
	v_lshlrev_b32_e32 v0, 4, v202
	v_and_b32_e32 v24, 0x70, v0
	v_readlane_b32 s1, v246, 0
	v_add_u32_e32 v0, 0x200, v202
	s_movk_i32 s0, 0x90
	s_waitcnt lgkmcnt(0)
	v_add_u32_e32 v1, s1, v24
	v_lshrrev_b32_e32 v28, 3, v0
	v_and_b32_e32 v2, 15, v202
	v_bfe_u32 v4, v202, 4, 2
	v_mov_b32_e32 v5, s1
	v_lshrrev_b32_e32 v0, 2, v202
	s_movk_i32 s1, 0xf0
	v_and_or_b32 v42, v0, s1, v2
	v_mad_u32_u24 v8, v2, s0, v5
	v_lshlrev_b32_e32 v2, 2, v4
	v_lshlrev_b32_e32 v0, 3, v4
	v_lshlrev_b32_e32 v9, 4, v4
	v_sub_u32_e32 v4, v42, v2
	v_cmp_lt_i32_e32 vcc, -1, v4
	v_cvt_f32_u32_e32 v43, v4
	v_xad_u32 v4, v2, -1, v42
	v_cmp_lt_i32_e64 s[4:5], -1, v4
	v_cvt_f32_u32_e32 v44, v4
	v_or_b32_e32 v4, 3, v2
	v_sub_u32_e32 v4, v42, v4
	v_cmp_lt_i32_e64 s[6:7], -1, v4
	v_cvt_f32_u32_e32 v46, v4
	v_or_b32_e32 v4, 17, v2
	v_sub_u32_e32 v11, v42, v4
	v_or_b32_e32 v4, 19, v2
	v_sub_u32_e32 v13, v42, v4
	v_or_b32_e32 v4, 33, v2
	v_sub_u32_e32 v15, v42, v4
	v_or_b32_e32 v4, 35, v2
	v_sub_u32_e32 v17, v42, v4
	v_or_b32_e32 v4, 49, v2
	v_sub_u32_e32 v19, v42, v4
	v_or_b32_e32 v4, 51, v2
	v_sub_u32_e32 v21, v42, v4
	v_or_b32_e32 v4, 0x41, v2
	v_sub_u32_e32 v23, v42, v4
	v_or_b32_e32 v4, 0x43, v2
	v_sub_u32_e32 v34, v42, v4
	v_or_b32_e32 v4, 0x51, v2
	v_sub_u32_e32 v36, v42, v4
	v_or_b32_e32 v4, 0x53, v2
	v_sub_u32_e32 v38, v42, v4
	v_or_b32_e32 v4, 0x61, v2
	v_sub_u32_e32 v40, v42, v4
	v_or_b32_e32 v4, 0x63, v2
	v_sub_u32_e32 v78, v42, v4
	v_or_b32_e32 v4, 0x71, v2
	v_or_b32_e32 v30, 0x42, v2
	v_sub_u32_e32 v84, v42, v4
	v_or_b32_e32 v4, 0x73, v2
	v_sub_u32_e32 v35, v42, v30
	v_or_b32_e32 v30, 0x50, v2
	v_sub_u32_e32 v80, v42, v4
	v_bfe_u32 v4, v202, 2, 2
	v_sub_u32_e32 v37, v42, v30
	v_or_b32_e32 v30, 0x52, v2
	v_or_b32_e32 v4, v2, v4
	s_movk_i32 s1, 0x7f
	v_sub_u32_e32 v39, v42, v30
	v_or_b32_e32 v30, 0x60, v2
	v_mad_u32_u24 v83, v4, s0, v5
	v_lshlrev_b32_e32 v4, 3, v202
	v_cmp_lt_u32_e64 s[12:13], s1, v202
	s_movk_i32 s1, 0xbf
	v_sub_u32_e32 v41, v42, v30
	v_or_b32_e32 v30, 0x62, v2
	v_and_b32_e32 v87, 24, v4
	v_add_u32_e32 v4, 1, v42
	v_cmp_lt_u32_e64 s[14:15], s1, v202
	s_movk_i32 s1, 0xff
	v_sub_u32_e32 v79, v42, v30
	v_or_b32_e32 v30, 0x70, v2
	v_cvt_f32_u32_e32 v75, v4
	v_mbcnt_lo_u32_b32 v4, -1, 0
	v_cmp_lt_u32_e64 s[16:17], s1, v202
	s_movk_i32 s1, 0x13f
	v_sub_u32_e32 v85, v42, v30
	v_or_b32_e32 v30, 0x72, v2
	v_mbcnt_hi_u32_b32 v4, -1, v4
	v_lshrrev_b32_e32 v26, 3, v202
	v_cmp_lt_u32_e64 s[18:19], s1, v202
	s_movk_i32 s1, 0x17f
	v_sub_u32_e32 v86, v42, v30
	v_and_b32_e32 v30, 64, v4
	v_mad_u32_u24 v7, v26, s0, v5
	v_cmp_lt_u32_e64 s[82:83], s1, v202
	s_movk_i32 s1, 0x1bf
	v_xor_b32_e32 v5, 16, v4
	v_add_u32_e32 v30, 64, v30
	v_cmp_lt_u32_e64 s[84:85], s1, v202
	v_cmp_lt_i32_e64 s[0:1], v5, v30
	v_mov_b32_e32 v25, 0
	s_add_u32 s94, s22, 0x95a4000
	v_cndmask_b32_e64 v5, v4, v5, s[0:1]
	v_lshlrev_b32_e32 v76, 2, v5
	v_xor_b32_e32 v5, 32, v4
	v_cmp_lt_i32_e64 s[0:1], v5, v30
	s_addc_u32 s95, s23, 0
	s_add_u32 s96, s22, 0xf8a4000
	v_cndmask_b32_e64 v4, v4, v5, s[0:1]
	v_lshlrev_b32_e32 v77, 2, v4
	v_lshl_add_u64 v[4:5], s[22:23], 0, v[24:25]
	s_mov_b64 s[0:1], 0xb6a4000
	v_lshl_add_u64 v[30:31], v[4:5], 0, s[0:1]
	s_mov_b64 s[0:1], 0xd7a4000
	v_lshl_add_u64 v[32:33], v[4:5], 0, s[0:1]
	v_readlane_b32 s0, v246, 60
	v_mov_b32_e32 v27, v25
	v_or_b32_e32 v10, 2, v2
	s_addc_u32 s97, s23, 0
	v_readlane_b32 s1, v246, 61
	s_mov_b32 s76, s0
	s_ashr_i32 s77, s0, 31
	v_sub_u32_e32 v10, v42, v10
	s_lshl_b64 s[0:1], s[76:77], 13
	v_lshlrev_b64 v[4:5], 7, v[26:27]
	v_cvt_f32_u32_e32 v45, v10
	v_cmp_lt_i32_e64 s[8:9], -1, v10
	v_or_b32_e32 v10, 16, v2
	v_or_b32_e32 v12, 18, v2
	v_or_b32_e32 v14, 32, v2
	v_or_b32_e32 v16, 34, v2
	v_or_b32_e32 v18, 48, v2
	v_or_b32_e32 v20, 50, v2
	v_or_b32_e32 v22, 64, v2
	v_lshl_add_u64 v[4:5], s[0:1], 0, v[4:5]
	v_sub_u32_e32 v10, v42, v10
	v_sub_u32_e32 v12, v42, v12
	v_sub_u32_e32 v14, v42, v14
	v_sub_u32_e32 v16, v42, v16
	v_sub_u32_e32 v18, v42, v18
	v_sub_u32_e32 v20, v42, v20
	v_sub_u32_e32 v22, v42, v22
	v_or_b32_e32 v4, v4, v24
	v_cvt_f32_u32_e32 v47, v10
	v_cvt_f32_u32_e32 v48, v11
	v_cvt_f32_u32_e32 v49, v12
	v_cvt_f32_u32_e32 v50, v13
	v_cvt_f32_u32_e32 v51, v14
	v_cvt_f32_u32_e32 v52, v15
	v_cvt_f32_u32_e32 v53, v16
	v_cvt_f32_u32_e32 v54, v17
	v_cvt_f32_u32_e32 v55, v18
	v_cvt_f32_u32_e32 v56, v19
	v_cvt_f32_u32_e32 v57, v20
	v_cvt_f32_u32_e32 v58, v21
	v_cvt_f32_u32_e32 v59, v22
	v_cvt_f32_u32_e32 v60, v23
	v_cvt_f32_u32_e32 v61, v35
	v_cvt_f32_u32_e32 v62, v34
	v_cvt_f32_u32_e32 v63, v37
	v_cvt_f32_u32_e32 v64, v36
	v_cvt_f32_u32_e32 v65, v39
	v_cvt_f32_u32_e32 v66, v38
	v_cvt_f32_u32_e32 v67, v41
	v_cvt_f32_u32_e32 v68, v40
	v_cvt_f32_u32_e32 v69, v79
	v_cvt_f32_u32_e32 v70, v78
	v_cvt_f32_u32_e32 v71, v85
	v_cvt_f32_u32_e32 v72, v84
	v_cvt_f32_u32_e32 v73, v86
	v_cvt_f32_u32_e32 v74, v80
	v_lshl_add_u64 v[4:5], s[22:23], 0, v[4:5]
	s_mov_b64 s[0:1], 0x17ba4000
	v_readlane_b32 s78, v246, 1
	v_cmp_lt_i32_e64 s[50:51], -1, v34
	v_cmp_lt_i32_e64 s[52:53], -1, v35
	v_lshl_add_u64 v[34:35], v[4:5], 0, s[0:1]
	s_ashr_i32 s1, s78, 31
	s_mov_b32 s0, s78
	v_mul_u32_u24_e32 v3, 0x90, v26
	v_mul_u32_u24_e32 v6, 0x90, v28
	v_readlane_b32 s79, v246, 2
	s_lshl_b64 s[86:87], s[0:1], 13
	s_mov_b32 s0, s76
	v_mov_b32_e32 v29, v25
	v_cmp_lt_u32_e64 s[10:11], 63, v202
	s_mov_b32 s3, 0
	v_cmp_lt_i32_e64 s[24:25], -1, v13
	v_cmp_lt_i32_e64 s[26:27], -1, v12
	v_cmp_lt_i32_e64 s[28:29], -1, v11
	v_cmp_lt_i32_e64 s[30:31], -1, v10
	v_cmp_lt_i32_e64 s[34:35], -1, v17
	v_cmp_lt_i32_e64 s[36:37], -1, v16
	v_cmp_lt_i32_e64 s[38:39], -1, v15
	v_cmp_lt_i32_e64 s[40:41], -1, v14
	v_cmp_lt_i32_e64 s[42:43], -1, v21
	v_cmp_lt_i32_e64 s[44:45], -1, v20
	v_cmp_lt_i32_e64 s[46:47], -1, v19
	v_cmp_lt_i32_e64 s[48:49], -1, v18
	v_cmp_lt_i32_e64 s[54:55], -1, v23
	v_cmp_lt_i32_e64 s[56:57], -1, v22
	v_cmp_lt_i32_e64 s[58:59], -1, v38
	v_cmp_lt_i32_e64 s[60:61], -1, v39
	v_cmp_lt_i32_e64 s[62:63], -1, v36
	v_cmp_lt_i32_e64 s[64:65], -1, v37
	v_cmp_lt_i32_e64 s[66:67], -1, v78
	v_cmp_lt_i32_e64 s[68:69], -1, v79
	v_cmp_lt_i32_e64 s[70:71], -1, v40
	v_cmp_lt_i32_e64 s[72:73], -1, v41
	v_cmp_lt_i32_e64 s[74:75], -1, v80
	s_lshl_b32 s33, s76, 7
	s_lshl_b32 s90, s78, 7
	v_mov_b32_e32 v27, 0x42800000
	v_add_u32_e32 v78, v1, v3
	v_add_u32_e32 v79, v1, v6
	v_add_u32_e32 v80, v7, v24
	v_lshlrev_b32_e32 v36, 1, v0
	v_mov_b32_e32 v37, v25
	v_add_u32_e32 v81, v8, v9
	v_mov_b32_e32 v82, 0x358637bd
	v_lshlrev_b32_e32 v38, 1, v2
	v_add_u32_e32 v83, v83, v87
	v_writelane_b32 v246, s0, 60
	s_mov_b32 s91, s76
	v_cmp_lt_i32_e64 s[76:77], -1, v86
	v_cmp_lt_i32_e64 s[78:79], -1, v84
	v_cmp_lt_i32_e64 s[80:81], -1, v85
	v_writelane_b32 v246, s1, 61
	s_branch .LBB0_723

.LBB0_870:
	v_bfe_u32 v247, v202, 8, 1
	v_mul_u32_u24_e32 v247, 0xc0, v247
	v_xor_b32_e32 v202, v202, v247
	v_readlane_b32 s0, v246, 4
	v_readlane_b32 s1, v246, 5
	s_cmp_lt_i32 s0, 6
	s_cselect_b64 s[0:1], -1, 0
	s_and_b64 s[2:3], s[0:1], s[2:3]
	s_andn2_b64 vcc, exec, s[2:3]
	s_cbranch_vccnz .LBB0_905
	s_add_u32 s2, s22, 0x119a4000
	s_addc_u32 s3, s23, 0
	s_add_u32 s6, s22, 0x580000
	s_addc_u32 s7, s23, 0
	s_movk_i32 s8, 0x80
	s_and_b64 s[4:5], s[68:69], exec
	s_cselect_b32 s33, s8, 0x84
	s_lshl_b32 s8, s33, 2
	s_cmp_lt_i32 s30, s8
	s_cselect_b64 s[4:5], -1, 0
	s_cmp_ge_i32 s30, s8
	v_readfirstlane_b32 s42, v202
	s_cbranch_scc1 .LBB0_873
	s_ashr_i32 s10, s30, 31
	s_lshr_b32 s10, s10, 29
	s_add_i32 s10, s30, s10
	s_ashr_i32 s11, s10, 3
	s_and_b32 s10, s10, -8
	s_sub_i32 s10, s30, s10
	s_lshr_b32 s9, s33, 1
	s_lshr_b32 s12, s10, 31
	s_or_b32 s9, s9, s12
	s_mul_i32 s9, s9, s10
	s_add_i32 s9, s9, s11
	s_ashr_i32 s10, s9, 31
	s_lshr_b32 s10, s10, 27
	s_add_i32 s10, s9, s10
	s_ashr_i32 s11, s10, 5
	s_lshl_b32 s12, s11, 3
	s_sub_i32 s11, s33, s12
	s_min_u32 s13, s11, 8
	s_andn2_b32 s10, s10, 31
	s_sub_i32 s9, s9, s10
	s_waitcnt lgkmcnt(0)
	v_cvt_f32_ubyte0_e32 v1, s13
	v_cvt_f32_i32_e32 v0, s9
	v_rcp_iflag_f32_e32 v2, v1
	s_ashr_i32 s10, s9, 30
	s_or_b32 s14, s10, 1
	v_mul_f32_e32 v2, v0, v2
	v_trunc_f32_e32 v2, v2
	v_fma_f32 v0, -v2, v1, v0
	v_cvt_i32_f32_e32 v2, v2
	v_cmp_ge_f32_e64 s[10:11], |v0|, v1
	s_and_b64 s[10:11], s[10:11], exec
	s_cselect_b32 s10, s14, 0
	v_readfirstlane_b32 s11, v2
	s_add_i32 s10, s11, s10
	s_mul_i32 s11, s10, s13
	s_sub_i32 s9, s9, s11
	s_sext_i32_i8 s9, s9
	s_add_i32 s24, s12, s9
	s_ashr_i32 s25, s24, 31
	s_lshl_b64 s[12:13], s[24:25], 19
	s_add_u32 s26, s2, s12
	s_sext_i32_i8 s65, s10
	s_addc_u32 s27, s3, s13
	s_bfe_i64 s[10:11], s[10:11], 0x80000
	s_lshl_b64 s[10:11], s[10:11], 19
	s_add_u32 s28, s6, s10
	s_addc_u32 s29, s7, s11
	s_andn2_b64 vcc, exec, s[4:5]
	s_cbranch_vccz .LBB0_874
	s_branch .LBB0_905
